# FoX tile loop: all eight K-fragment LDS reads issued right after the barrier into distinct registers; QK MFMAs use counted lgkmcnt waits
# baseline (speedup 1.0000x reference)
.LBB0_1689:
	s_and_b32 s2, s18, 1
	s_mul_i32 s3, s2, 0x2400
	s_add_i32 s19, s3, 0
	s_mulk_i32 s2, 0xdd00
	s_add_i32 s16, s19, s2
	v_add3_u32 v0, s19, v123, v124
	s_waitcnt vmcnt(1)
	ds_write_b128 v0, v[96:99]
	s_waitcnt vmcnt(0)
	ds_write_b128 v0, v[100:103] offset:18432
	s_and_saveexec_b64 s[2:3], s[0:1]
	v_mul_f32_e32 v121, 0x3fb8aa3b, v220
	v_lshl_add_u32 v0, v110, 2, s16
	ds_write_b32 v0, v121 offset:36864
	s_or_b64 exec, exec, s[2:3]
	v_mov_b32_e32 v0, s16
	s_waitcnt lgkmcnt(0)
	s_barrier
	ds_read_b32 v0, v0 offset:37116
	v_add3_u32 v225, s19, v126, v114
	ds_read_b128 v[240:243], v225
	ds_read_b128 v[244:247], v225 offset:32
	ds_read_b128 v[144:147], v225 offset:4608
	ds_read_b128 v[148:151], v225 offset:4640
	ds_read_b128 v[152:155], v225 offset:64
	ds_read_b128 v[156:159], v225 offset:96
	ds_read_b128 v[160:163], v225 offset:4672
	ds_read_b128 v[164:167], v225 offset:4704
	s_waitcnt lgkmcnt(8)
	v_cmp_gt_f32_e32 vcc, v0, v122
	v_mov_b32_e32 v0, 17
	s_cbranch_vccnz .LBB0_1703
	s_cmp_lt_i32 s9, 1
	s_cbranch_scc1 .LBB0_1696
	s_add_i32 s2, s9, -1
	v_mad_u64_u32 v[2:3], s[2:3], s2, v230, v[116:117]
	global_load_dwordx4 v[96:99], v[2:3], off offset:2048
	global_load_dwordx4 v[100:103], v[2:3], off offset:2560
	s_and_saveexec_b64 s[2:3], s[0:1]
	s_cbranch_execz .LBB0_1695
	v_lshl_add_u64 v[2:3], v[118:119], 0, s[94:95]
	v_lshl_add_u64 v[2:3], v[2:3], 4, s[10:11]
	global_load_dword v220, v[2:3], off

.LBB0_1696:
	s_add_i32 s2, s94, 64
	v_cmp_le_i32_e32 vcc, s2, v125
	v_mov_b32_e32 v0, 19
	s_and_saveexec_b64 s[14:15], vcc
	s_cbranch_execz .LBB0_1702
	v_add3_u32 v0, s19, v126, v114
	v_sub_f32_e32 v64, v113, v115
	v_mov_b32_e32 v65, v64
	v_mov_b32_e32 v66, v64
	v_mov_b32_e32 v67, v64
	v_mov_b32_e32 v68, v64
	v_mov_b32_e32 v69, v64
	v_mov_b32_e32 v70, v64
	v_mov_b32_e32 v71, v64
	v_mov_b32_e32 v72, v64
	v_mov_b32_e32 v73, v64
	v_mov_b32_e32 v74, v64
	v_mov_b32_e32 v75, v64
	v_mov_b32_e32 v76, v64
	v_mov_b32_e32 v77, v64
	v_mov_b32_e32 v78, v64
	v_mov_b32_e32 v79, v64
	v_lshl_add_u32 v142, v111, 2, s16
	s_add_i32 s2, s94, 0x7f
	s_waitcnt lgkmcnt(7)
	v_mfma_f32_32x32x16_bf16 v[48:63], v[240:243], v[80:83], v[64:79]
	v_cmp_gt_i32_e32 vcc, s2, v120
	s_waitcnt lgkmcnt(5)
	v_mfma_f32_32x32x16_bf16 v[64:79], v[144:147], v[80:83], v[64:79]
	v_mfma_f32_32x32x16_bf16 v[48:63], v[244:247], v[84:87], v[48:63]
	s_waitcnt lgkmcnt(4)
	v_mfma_f32_32x32x16_bf16 v[64:79], v[148:151], v[84:87], v[64:79]
	s_waitcnt lgkmcnt(3)
	v_mfma_f32_32x32x16_bf16 v[48:63], v[152:155], v[88:91], v[48:63]
	s_waitcnt lgkmcnt(1)
	v_mfma_f32_32x32x16_bf16 v[64:79], v[160:163], v[88:91], v[64:79]
	v_mfma_f32_32x32x16_bf16 v[48:63], v[156:159], v[92:95], v[48:63]
	ds_read_b128 v[6:9], v142 offset:36960
	ds_read_b128 v[130:133], v142 offset:36928
	ds_read_b128 v[134:137], v142 offset:36864
	ds_read_b128 v[138:141], v142 offset:36896
	s_waitcnt lgkmcnt(4)
	v_mfma_f32_32x32x16_bf16 v[64:79], v[164:167], v[92:95], v[64:79]
	s_waitcnt lgkmcnt(3)
	s_nop 4
	v_sub_f32_e32 v15, v63, v9
	v_sub_f32_e32 v14, v62, v8
	v_sub_f32_e32 v13, v61, v7
	v_sub_f32_e32 v12, v60, v6
	s_waitcnt lgkmcnt(2)
	v_sub_f32_e32 v11, v59, v133
	v_sub_f32_e32 v10, v58, v132
	v_sub_f32_e32 v9, v57, v131
	v_sub_f32_e32 v8, v56, v130
	s_waitcnt lgkmcnt(0)
	v_sub_f32_e32 v7, v55, v141
	v_sub_f32_e32 v6, v54, v140
	ds_read_b128 v[54:57], v142 offset:37088
	ds_read_b128 v[58:61], v142 offset:37056
	ds_read_b128 v[104:107], v142 offset:36992
	ds_read_b128 v[130:133], v142 offset:37024
	v_sub_f32_e32 v5, v53, v139
	v_sub_f32_e32 v4, v52, v138
	v_sub_f32_e32 v3, v51, v137
	v_sub_f32_e32 v2, v50, v136
	v_sub_f32_e32 v53, v49, v135
	v_sub_f32_e32 v0, v48, v134
	s_waitcnt lgkmcnt(3)
	v_sub_f32_e32 v49, v79, v57
	v_sub_f32_e32 v48, v78, v56
	v_sub_f32_e32 v51, v77, v55
	v_sub_f32_e32 v50, v76, v54
	s_waitcnt lgkmcnt(2)
	v_sub_f32_e32 v55, v75, v61
	v_sub_f32_e32 v52, v74, v60
	v_sub_f32_e32 v57, v73, v59
	v_sub_f32_e32 v54, v72, v58
	s_waitcnt lgkmcnt(0)
	v_sub_f32_e32 v59, v71, v133
	v_sub_f32_e32 v56, v70, v132
	v_sub_f32_e32 v61, v69, v131
	v_sub_f32_e32 v58, v68, v130
	v_sub_f32_e32 v63, v67, v107
	v_sub_f32_e32 v60, v66, v106
	v_sub_f32_e32 v65, v65, v105
	v_sub_f32_e32 v62, v64, v104
	s_and_saveexec_b64 s[16:17], vcc
	s_cbranch_execz .LBB0_1699
	v_add_u32_e32 v64, s94, v111
	v_add_u32_e32 v67, 0x60, v64
	v_add_u32_e32 v66, 64, v64
	v_cmp_le_i32_e64 s[2:3], v67, v112
	v_cmp_le_i32_e32 vcc, v66, v112
	s_nop 0
	v_cndmask_b32_e64 v62, v236, v62, s[2:3]
	v_cmp_lt_i32_e64 s[2:3], v66, v112
	v_add_u32_e32 v66, 0x61, v64
	v_cndmask_b32_e32 v0, v236, v0, vcc
	v_cmp_le_i32_e32 vcc, v66, v112
	v_add_u32_e32 v66, 0x42, v64
	v_cndmask_b32_e64 v53, v236, v53, s[2:3]
	v_cndmask_b32_e32 v65, v236, v65, vcc
	v_cmp_le_i32_e32 vcc, v66, v112
	v_add_u32_e32 v66, 0x62, v64
	s_nop 0
	v_cndmask_b32_e32 v2, v236, v2, vcc
	v_cmp_le_i32_e32 vcc, v66, v112
	v_add_u32_e32 v66, 0x43, v64
	s_nop 0
	v_cndmask_b32_e32 v60, v236, v60, vcc
	v_cmp_le_i32_e32 vcc, v66, v112
	v_add_u32_e32 v66, 0x63, v64
	s_nop 0
	v_cndmask_b32_e32 v3, v236, v3, vcc
	v_cmp_le_i32_e32 vcc, v66, v112
	v_add_u32_e32 v66, 0x48, v64
	s_nop 0
	v_cndmask_b32_e32 v63, v236, v63, vcc
	v_cmp_le_i32_e32 vcc, v66, v112
	v_add_u32_e32 v66, 0x68, v64
	s_nop 0
	v_cndmask_b32_e32 v4, v236, v4, vcc
	v_cmp_le_i32_e32 vcc, v66, v112
	v_add_u32_e32 v66, 0x49, v64
	s_nop 0
	v_cndmask_b32_e32 v58, v236, v58, vcc
	v_cmp_le_i32_e32 vcc, v66, v112
	v_add_u32_e32 v66, 0x69, v64
	s_nop 0
	v_cndmask_b32_e32 v5, v236, v5, vcc
	v_cmp_le_i32_e32 vcc, v66, v112
	v_add_u32_e32 v66, 0x4a, v64
	s_nop 0
	v_cndmask_b32_e32 v61, v236, v61, vcc
	v_cmp_le_i32_e32 vcc, v66, v112
	v_add_u32_e32 v66, 0x6a, v64
	s_nop 0
	v_cndmask_b32_e32 v6, v236, v6, vcc
	v_cmp_le_i32_e32 vcc, v66, v112
	v_add_u32_e32 v66, 0x4b, v64
	s_nop 0
	v_cndmask_b32_e32 v56, v236, v56, vcc
	v_cmp_le_i32_e32 vcc, v66, v112
	v_add_u32_e32 v66, 0x6b, v64
	s_nop 0
	v_cndmask_b32_e32 v7, v236, v7, vcc
	v_cmp_le_i32_e32 vcc, v66, v112
	v_add_u32_e32 v66, 0x50, v64
	s_nop 0
	v_cndmask_b32_e32 v59, v236, v59, vcc
	v_cmp_le_i32_e32 vcc, v66, v112
	v_add_u32_e32 v66, 0x70, v64
	s_nop 0
	v_cndmask_b32_e32 v8, v236, v8, vcc
	v_cmp_le_i32_e32 vcc, v66, v112
	v_add_u32_e32 v66, 0x51, v64
	s_nop 0
	v_cndmask_b32_e32 v54, v236, v54, vcc
	v_cmp_le_i32_e32 vcc, v66, v112
	v_add_u32_e32 v66, 0x71, v64
	s_nop 0
	v_cndmask_b32_e32 v9, v236, v9, vcc
	v_cmp_le_i32_e32 vcc, v66, v112
	v_add_u32_e32 v66, 0x52, v64
	s_nop 0
	v_cndmask_b32_e32 v57, v236, v57, vcc
	v_cmp_le_i32_e32 vcc, v66, v112
	v_add_u32_e32 v66, 0x72, v64
	s_nop 0
	v_cndmask_b32_e32 v10, v236, v10, vcc
	v_cmp_le_i32_e32 vcc, v66, v112
	v_add_u32_e32 v66, 0x53, v64
	s_nop 0
	v_cndmask_b32_e32 v52, v236, v52, vcc
	v_cmp_le_i32_e32 vcc, v66, v112
	v_add_u32_e32 v66, 0x73, v64
	s_nop 0
	v_cndmask_b32_e32 v11, v236, v11, vcc
	v_cmp_le_i32_e32 vcc, v66, v112
	v_add_u32_e32 v66, 0x58, v64
	s_nop 0
	v_cndmask_b32_e32 v55, v236, v55, vcc
	v_cmp_le_i32_e32 vcc, v66, v112
	v_add_u32_e32 v66, 0x78, v64
	s_nop 0
	v_cndmask_b32_e32 v12, v236, v12, vcc
	v_cmp_le_i32_e32 vcc, v66, v112
	v_add_u32_e32 v66, 0x59, v64
	s_nop 0
	v_cndmask_b32_e32 v50, v236, v50, vcc
	v_cmp_le_i32_e32 vcc, v66, v112
	v_add_u32_e32 v66, 0x79, v64
	s_nop 0
	v_cndmask_b32_e32 v13, v236, v13, vcc
	v_cmp_le_i32_e32 vcc, v66, v112
	v_add_u32_e32 v66, 0x5a, v64
	s_nop 0
	v_cndmask_b32_e32 v51, v236, v51, vcc
	v_cmp_le_i32_e32 vcc, v66, v112
	v_add_u32_e32 v66, 0x7a, v64
	s_nop 0
	v_cndmask_b32_e32 v14, v236, v14, vcc
	v_cmp_le_i32_e32 vcc, v66, v112
	v_add_u32_e32 v66, 0x5b, v64
	v_add_u32_e32 v64, 0x7b, v64
	v_cndmask_b32_e32 v48, v236, v48, vcc
	v_cmp_le_i32_e32 vcc, v66, v112
	s_nop 1
	v_cndmask_b32_e32 v15, v236, v15, vcc
	v_cmp_le_i32_e32 vcc, v64, v112
	s_nop 1
	v_cndmask_b32_e32 v49, v236, v49, vcc
